# v46 + diff-attention loops: second-half pre-write barrier also removed (V staging loads retargeted to free VGPRs, V written after the loop-bottom barrier)
# baseline (speedup 1.0000x reference)
.LBB0_683:
	ds_read_b128 v[64:67], v170 offset:49152
	ds_read_b128 v[68:71], v170 offset:57344
	v_add_f32_e32 v144, 0, v145
	v_add_f32_e32 v144, v158, v144
	v_add_f32_e32 v144, v146, v144
	s_waitcnt lgkmcnt(1)
	v_mfma_f32_32x32x16_bf16 v[80:95], v[64:67], v[100:103], 0
	v_add_f32_e32 v144, v159, v144
	v_add_f32_e32 v144, v147, v144
	ds_read_b128 v[204:207], v186 offset:49152
	ds_read_b128 v[226:229], v186 offset:57344
	v_add_f32_e32 v144, v200, v144
	v_add_f32_e32 v144, v157, v144
	v_add_f32_e32 v144, v203, v144
	v_add_f32_e32 v144, v149, v144
	s_waitcnt lgkmcnt(2)
	v_mfma_f32_32x32x16_bf16 v[64:79], v[68:71], v[100:103], 0
	v_add_f32_e32 v144, v153, v144
	v_add_f32_e32 v144, v150, v144
	v_add_f32_e32 v144, v154, v144
	v_exp_f32_e32 v142, v142
	v_add_f32_e32 v144, v151, v144
	v_exp_f32_e32 v143, v143
	v_add_f32_e32 v144, v155, v144
	s_waitcnt lgkmcnt(1)
	v_mfma_f32_32x32x16_bf16 v[80:95], v[204:207], v[108:111], v[80:95]
	v_exp_f32_e32 v140, v140
	v_add_f32_e32 v144, v152, v144
	v_exp_f32_e32 v141, v141
	v_add_f32_e32 v144, v156, v144
	v_exp_f32_e32 v136, v136
	v_add_f32_e32 v144, v142, v144
	v_exp_f32_e32 v137, v137
	s_waitcnt lgkmcnt(0)
	v_mfma_f32_32x32x16_bf16 v[64:79], v[226:229], v[108:111], v[64:79]
	ds_read_b128 v[204:207], v175 offset:49152
	ds_read_b128 v[226:229], v175 offset:57344
	v_add_f32_e32 v144, v143, v144
	v_exp_f32_e32 v132, v132
	v_add_f32_e32 v144, v140, v144
	v_exp_f32_e32 v133, v133
	v_add_f32_e32 v144, v141, v144
	v_exp_f32_e32 v130, v130
	s_waitcnt lgkmcnt(1)
	v_mfma_f32_32x32x16_bf16 v[80:95], v[204:207], v[96:99], v[80:95]
	v_add_f32_e32 v144, v136, v144
	v_exp_f32_e32 v131, v131
	v_add_f32_e32 v144, v137, v144
	v_exp_f32_e32 v138, v138
	v_add_f32_e32 v144, v132, v144
	v_exp_f32_e32 v139, v139
	v_add_f32_e32 v144, v133, v144
	s_waitcnt lgkmcnt(0)
	v_mfma_f32_32x32x16_bf16 v[64:79], v[226:229], v[96:99], v[64:79]
	ds_read_b128 v[204:207], v187 offset:49152
	ds_read_b128 v[226:229], v187 offset:57344
	v_exp_f32_e32 v134, v134
	v_add_f32_e32 v144, v130, v144
	v_exp_f32_e32 v135, v135
	v_add_f32_e32 v144, v131, v144
	v_exp_f32_e32 v128, v128
	v_add_f32_e32 v144, v138, v144
	s_waitcnt lgkmcnt(1)
	v_mfma_f32_32x32x16_bf16 v[80:95], v[204:207], v[104:107], v[80:95]
	v_exp_f32_e32 v129, v129
	v_add_f32_e32 v144, v139, v144
	v_add_f32_e32 v144, v134, v144
	v_add_f32_e32 v144, v135, v144
	v_add_f32_e32 v144, v128, v144
	v_add_f32_e32 v189, v129, v144
	v_mov_b32_e32 v198, v189
	s_waitcnt lgkmcnt(0)
	v_mfma_f32_32x32x16_bf16 v[64:79], v[226:229], v[104:107], v[64:79]
	v_cvt_pk_bf16_f32 v144, v145, v158
	v_cvt_pk_bf16_f32 v145, v146, v159
	v_cvt_pk_bf16_f32 v146, v147, v200
	v_permlane32_swap_b32_e32 v189, v198
	v_cvt_pk_bf16_f32 v147, v157, v203
	v_permlane32_swap_b32_e32 v144, v146
	v_cvt_pk_bf16_f32 v200, v149, v153
	v_cvt_pk_bf16_f32 v201, v150, v154
	v_cvt_pk_bf16_f32 v202, v151, v155
	v_cvt_pk_bf16_f32 v203, v152, v156
	v_cvt_pk_bf16_f32 v150, v142, v143
	v_cvt_pk_bf16_f32 v151, v140, v141
	v_cvt_pk_bf16_f32 v152, v136, v137
	v_cvt_pk_bf16_f32 v153, v132, v133
	v_cvt_pk_bf16_f32 v154, v130, v131
	v_cvt_pk_bf16_f32 v155, v138, v139
	v_cvt_pk_bf16_f32 v156, v134, v135
	v_cvt_pk_bf16_f32 v157, v128, v129
	v_permlane32_swap_b32_e32 v145, v147
	v_permlane32_swap_b32_e32 v200, v202
	v_permlane32_swap_b32_e32 v201, v203
	v_permlane32_swap_b32_e32 v150, v152
	v_permlane32_swap_b32_e32 v151, v153
	v_permlane32_swap_b32_e32 v154, v156
	v_permlane32_swap_b32_e32 v155, v157
	v_add_co_u32_e32 v128, vcc, s33, v162
	s_nop 1
	v_addc_co_u32_e32 v129, vcc, -1, v163, vcc
	v_add_co_u32_e32 v132, vcc, s70, v162
	s_nop 1
	v_addc_co_u32_e32 v133, vcc, -1, v163, vcc
	v_add_co_u32_e32 v136, vcc, s71, v162
	global_load_dwordx4 v[240:243], v[128:129], off
	s_nop 0
	global_load_dwordx4 v[244:247], v[132:133], off
	v_addc_co_u32_e32 v137, vcc, -1, v163, vcc
	v_add_co_u32_e32 v140, vcc, s72, v162
	s_nop 1
	v_addc_co_u32_e32 v141, vcc, -1, v163, vcc
	global_load_dwordx4 v[136:139], v[136:137], off
	s_nop 0
	global_load_dwordx4 v[140:143], v[140:141], off
	ds_read_b64_tr_b16 v[204:205], v169 offset:0
	ds_read_b64_tr_b16 v[206:207], v169 offset:0x800
	ds_read_b64_tr_b16 v[226:227], v169 offset:0x1000
	ds_read_b64_tr_b16 v[228:229], v169 offset:0x1800
	ds_read_b64_tr_b16 v[230:231], v169 offset:0x2000
	ds_read_b64_tr_b16 v[232:233], v169 offset:0x2800
	ds_read_b64_tr_b16 v[234:235], v169 offset:0x3000
	ds_read_b64_tr_b16 v[236:237], v169 offset:0x3800
	s_nop 0
	s_waitcnt lgkmcnt(6)
	v_mfma_f32_32x32x16_bf16 v[0:15], v[144:147], v[204:207], v[0:15]
	ds_read_b64_tr_b16 v[204:205], v169 offset:0x200
	ds_read_b64_tr_b16 v[206:207], v169 offset:0xa00
	s_waitcnt lgkmcnt(6)
	v_mfma_f32_32x32x16_bf16 v[0:15], v[200:203], v[226:229], v[0:15]
	ds_read_b64_tr_b16 v[226:227], v169 offset:0x1200
	ds_read_b64_tr_b16 v[228:229], v169 offset:0x1a00
	s_waitcnt lgkmcnt(6)
	v_mfma_f32_32x32x16_bf16 v[0:15], v[150:153], v[230:233], v[0:15]
	ds_read_b64_tr_b16 v[230:231], v169 offset:0x2200
	ds_read_b64_tr_b16 v[232:233], v169 offset:0x2a00
	s_waitcnt lgkmcnt(6)
	v_mfma_f32_32x32x16_bf16 v[0:15], v[154:157], v[234:237], v[0:15]
	ds_read_b64_tr_b16 v[234:235], v169 offset:0x3200
	ds_read_b64_tr_b16 v[236:237], v169 offset:0x3a00
	s_waitcnt lgkmcnt(6)
	v_mfma_f32_32x32x16_bf16 v[48:63], v[144:147], v[204:207], v[48:63]
	ds_read_b64_tr_b16 v[204:205], v169 offset:0x400
	ds_read_b64_tr_b16 v[206:207], v169 offset:0xc00
	s_waitcnt lgkmcnt(6)
	v_mfma_f32_32x32x16_bf16 v[48:63], v[200:203], v[226:229], v[48:63]
	ds_read_b64_tr_b16 v[226:227], v169 offset:0x1400
	ds_read_b64_tr_b16 v[228:229], v169 offset:0x1c00
	s_waitcnt lgkmcnt(6)
	v_mfma_f32_32x32x16_bf16 v[48:63], v[150:153], v[230:233], v[48:63]
	ds_read_b64_tr_b16 v[230:231], v169 offset:0x2400
	ds_read_b64_tr_b16 v[232:233], v169 offset:0x2c00
	s_waitcnt lgkmcnt(6)
	v_mfma_f32_32x32x16_bf16 v[48:63], v[154:157], v[234:237], v[48:63]
	ds_read_b64_tr_b16 v[234:235], v169 offset:0x3400
	ds_read_b64_tr_b16 v[236:237], v169 offset:0x3c00
	s_waitcnt lgkmcnt(6)
	v_mfma_f32_32x32x16_bf16 v[32:47], v[144:147], v[204:207], v[32:47]
	ds_read_b64_tr_b16 v[204:205], v169 offset:0x600
	ds_read_b64_tr_b16 v[206:207], v169 offset:0xe00
	s_waitcnt lgkmcnt(6)
	v_mfma_f32_32x32x16_bf16 v[32:47], v[200:203], v[226:229], v[32:47]
	ds_read_b64_tr_b16 v[226:227], v169 offset:0x1600
	ds_read_b64_tr_b16 v[228:229], v169 offset:0x1e00
	s_waitcnt lgkmcnt(6)
	v_mfma_f32_32x32x16_bf16 v[32:47], v[150:153], v[230:233], v[32:47]
	ds_read_b64_tr_b16 v[230:231], v169 offset:0x2600
	ds_read_b64_tr_b16 v[232:233], v169 offset:0x2e00
	s_waitcnt lgkmcnt(6)
	v_mfma_f32_32x32x16_bf16 v[32:47], v[154:157], v[234:237], v[32:47]
	ds_read_b64_tr_b16 v[234:235], v169 offset:0x3600
	ds_read_b64_tr_b16 v[236:237], v169 offset:0x3e00
	s_waitcnt lgkmcnt(6)
	v_mfma_f32_32x32x16_bf16 v[16:31], v[144:147], v[204:207], v[16:31]
	v_max_f32_e32 v144, v81, v81
	v_max_f32_e32 v145, v80, v80
	v_max_f32_e32 v144, v145, v144
	v_max3_f32 v144, v144, v82, v83
	v_max3_f32 v144, v144, v84, v85
	v_max3_f32 v144, v144, v86, v87
	v_max3_f32 v144, v144, v88, v89
	v_max3_f32 v144, v144, v90, v91
	v_max3_f32 v144, v144, v92, v93
	s_waitcnt lgkmcnt(4)
	v_mfma_f32_32x32x16_bf16 v[16:31], v[200:203], v[226:229], v[16:31]
	v_max3_f32 v144, v144, v94, v95
	v_max3_f32 v144, v144, v64, v65
	v_max3_f32 v144, v144, v66, v67
	v_max3_f32 v144, v144, v68, v69
	v_max3_f32 v144, v144, v70, v71
	v_max3_f32 v144, v144, v72, v73
	v_max3_f32 v144, v144, v74, v75
	v_max3_f32 v144, v144, v76, v77
	s_waitcnt lgkmcnt(2)
	v_mfma_f32_32x32x16_bf16 v[16:31], v[150:153], v[230:233], v[16:31]
	v_max3_f32 v144, v144, v78, v79
	v_mov_b32_e32 v145, v144
	s_nop 1
	v_permlane32_swap_b32_e32 v144, v145
	v_max_f32_e32 v145, v145, v145
	v_max_f32_e32 v144, v144, v144
	v_max_f32_e32 v144, v144, v145
	v_sub_f32_e32 v145, v144, v148
	v_cmp_ge_f32_e32 vcc, s49, v145
	v_max_f32_e32 v145, v148, v148
	v_max_f32_e32 v144, v145, v144
	s_waitcnt lgkmcnt(0)
	v_mfma_f32_32x32x16_bf16 v[16:31], v[154:157], v[234:237], v[16:31]
	v_sub_f32_e32 v145, v148, v144
	v_mul_f32_e32 v145, 0x3e38aa3b, v145
	v_exp_f32_e32 v145, v145
	s_cmp_eq_u64 vcc, exec
	s_cselect_b64 s[0:1], -1, 0
	s_waitcnt vmcnt(4)
	v_cndmask_b32_e64 v199, v145, 1.0, s[0:1]
	v_cmp_gt_f32_e32 vcc, 1.0, v199
	s_waitcnt vmcnt(7)
	s_waitcnt vmcnt(6)
	s_waitcnt vmcnt(5)
	ds_write_b128 v171, v[116:119] offset:32768
	s_waitcnt vmcnt(4)
	ds_write_b128 v172, v[124:127] offset:32768
	s_cbranch_vccz .LBB0_687
	s_and_saveexec_b64 s[28:29], s[6:7]
	ds_write_b32 v166, v199 offset:128
	s_or_b64 exec, exec, s[28:29]
	s_waitcnt lgkmcnt(0)
	v_add_u32_e32 v145, v161, v178
	ds_read_b128 v[150:153], v145 offset:224
	ds_read_b128 v[154:157], v145 offset:192
	ds_read_b128 v[200:203], v145 offset:160
	ds_read_b128 v[204:207], v145 offset:128
	s_waitcnt lgkmcnt(3)
	v_pk_mul_f32 v[12:13], v[12:13], v[150:151]
	s_waitcnt lgkmcnt(2)
	v_pk_mul_f32 v[8:9], v[8:9], v[154:155]
	s_waitcnt lgkmcnt(1)
	v_pk_mul_f32 v[4:5], v[4:5], v[200:201]
	v_pk_mul_f32 v[14:15], v[14:15], v[152:153]
	v_pk_mul_f32 v[10:11], v[10:11], v[156:157]
	v_pk_mul_f32 v[6:7], v[6:7], v[202:203]
	s_waitcnt lgkmcnt(0)
	v_pk_mul_f32 v[2:3], v[2:3], v[206:207]
	v_pk_mul_f32 v[0:1], v[0:1], v[204:205]
	v_pk_mul_f32 v[60:61], v[60:61], v[150:151]
	v_pk_mul_f32 v[56:57], v[56:57], v[154:155]
	v_pk_mul_f32 v[52:53], v[52:53], v[200:201]
	v_pk_mul_f32 v[62:63], v[62:63], v[152:153]
	v_pk_mul_f32 v[58:59], v[58:59], v[156:157]
	v_pk_mul_f32 v[54:55], v[54:55], v[202:203]
	v_pk_mul_f32 v[50:51], v[50:51], v[206:207]
	v_pk_mul_f32 v[48:49], v[48:49], v[204:205]
	v_pk_mul_f32 v[44:45], v[44:45], v[150:151]
	v_pk_mul_f32 v[40:41], v[40:41], v[154:155]
	v_pk_mul_f32 v[36:37], v[36:37], v[200:201]
	v_pk_mul_f32 v[46:47], v[46:47], v[152:153]
	v_pk_mul_f32 v[42:43], v[42:43], v[156:157]
	v_pk_mul_f32 v[38:39], v[38:39], v[202:203]
	v_pk_mul_f32 v[34:35], v[34:35], v[206:207]
	v_pk_mul_f32 v[32:33], v[32:33], v[204:205]
	v_pk_mul_f32 v[28:29], v[28:29], v[150:151]
	v_pk_mul_f32 v[24:25], v[24:25], v[154:155]
	v_pk_mul_f32 v[20:21], v[20:21], v[200:201]
	v_pk_mul_f32 v[30:31], v[30:31], v[152:153]
	v_pk_mul_f32 v[26:27], v[26:27], v[156:157]
	v_pk_mul_f32 v[22:23], v[22:23], v[202:203]
	v_pk_mul_f32 v[18:19], v[18:19], v[206:207]
	v_pk_mul_f32 v[16:17], v[16:17], v[204:205]

.LBB0_689:
	s_waitcnt lgkmcnt(0)
	ds_read_b64_tr_b16 v[204:205], v168 offset:0
	ds_read_b64_tr_b16 v[206:207], v168 offset:0x800
	ds_read_b64_tr_b16 v[226:227], v168 offset:0x1000
	ds_read_b64_tr_b16 v[228:229], v168 offset:0x1800
	ds_read_b64_tr_b16 v[230:231], v168 offset:0x2000
	ds_read_b64_tr_b16 v[232:233], v168 offset:0x2800
	ds_read_b64_tr_b16 v[234:235], v168 offset:0x3000
	ds_read_b64_tr_b16 v[236:237], v168 offset:0x3800
	s_nop 0
	s_waitcnt lgkmcnt(6)
	v_mfma_f32_32x32x16_bf16 v[0:15], v[144:147], v[204:207], v[0:15]
	ds_read_b64_tr_b16 v[204:205], v168 offset:0x200
	ds_read_b64_tr_b16 v[206:207], v168 offset:0xa00
	s_waitcnt lgkmcnt(6)
	v_mfma_f32_32x32x16_bf16 v[0:15], v[148:151], v[226:229], v[0:15]
	ds_read_b64_tr_b16 v[226:227], v168 offset:0x1200
	ds_read_b64_tr_b16 v[228:229], v168 offset:0x1a00
	s_waitcnt lgkmcnt(6)
	v_mfma_f32_32x32x16_bf16 v[0:15], v[152:155], v[230:233], v[0:15]
	ds_read_b64_tr_b16 v[230:231], v168 offset:0x2200
	ds_read_b64_tr_b16 v[232:233], v168 offset:0x2a00
	s_waitcnt lgkmcnt(6)
	v_mfma_f32_32x32x16_bf16 v[0:15], v[156:159], v[234:237], v[0:15]
	ds_read_b64_tr_b16 v[234:235], v168 offset:0x3200
	ds_read_b64_tr_b16 v[236:237], v168 offset:0x3a00
	s_waitcnt lgkmcnt(6)
	v_mfma_f32_32x32x16_bf16 v[48:63], v[144:147], v[204:207], v[48:63]
	ds_read_b64_tr_b16 v[204:205], v168 offset:0x400
	ds_read_b64_tr_b16 v[206:207], v168 offset:0xc00
	s_waitcnt lgkmcnt(6)
	v_mfma_f32_32x32x16_bf16 v[48:63], v[148:151], v[226:229], v[48:63]
	ds_read_b64_tr_b16 v[226:227], v168 offset:0x1400
	ds_read_b64_tr_b16 v[228:229], v168 offset:0x1c00
	s_waitcnt lgkmcnt(6)
	v_mfma_f32_32x32x16_bf16 v[48:63], v[152:155], v[230:233], v[48:63]
	ds_read_b64_tr_b16 v[230:231], v168 offset:0x2400
	ds_read_b64_tr_b16 v[232:233], v168 offset:0x2c00
	s_waitcnt lgkmcnt(6)
	v_mfma_f32_32x32x16_bf16 v[48:63], v[156:159], v[234:237], v[48:63]
	ds_read_b64_tr_b16 v[234:235], v168 offset:0x3400
	ds_read_b64_tr_b16 v[236:237], v168 offset:0x3c00
	s_waitcnt lgkmcnt(6)
	v_mfma_f32_32x32x16_bf16 v[32:47], v[144:147], v[204:207], v[32:47]
	ds_read_b64_tr_b16 v[204:205], v168 offset:0x600
	ds_read_b64_tr_b16 v[206:207], v168 offset:0xe00
	s_waitcnt lgkmcnt(6)
	v_mfma_f32_32x32x16_bf16 v[32:47], v[148:151], v[226:229], v[32:47]
	ds_read_b64_tr_b16 v[226:227], v168 offset:0x1600
	ds_read_b64_tr_b16 v[228:229], v168 offset:0x1e00
	s_waitcnt lgkmcnt(6)
	v_mfma_f32_32x32x16_bf16 v[32:47], v[152:155], v[230:233], v[32:47]
	ds_read_b64_tr_b16 v[230:231], v168 offset:0x2600
	ds_read_b64_tr_b16 v[232:233], v168 offset:0x2e00
	s_waitcnt lgkmcnt(6)
	v_mfma_f32_32x32x16_bf16 v[32:47], v[156:159], v[234:237], v[32:47]
	ds_read_b64_tr_b16 v[234:235], v168 offset:0x3600
	ds_read_b64_tr_b16 v[236:237], v168 offset:0x3e00
	s_waitcnt lgkmcnt(6)
	v_mfma_f32_32x32x16_bf16 v[16:31], v[144:147], v[204:207], v[16:31]
	v_max_f32_e32 v144, v81, v81
	v_max_f32_e32 v145, v80, v80
	v_max_f32_e32 v144, v145, v144
	v_max3_f32 v144, v144, v82, v83
	v_max3_f32 v144, v144, v84, v85
	v_max3_f32 v144, v144, v86, v87
	v_max3_f32 v144, v144, v88, v89
	v_max3_f32 v144, v144, v90, v91
	v_max3_f32 v144, v144, v92, v93
	s_waitcnt lgkmcnt(4)
	v_mfma_f32_32x32x16_bf16 v[16:31], v[148:151], v[226:229], v[16:31]
	v_max3_f32 v144, v144, v94, v95
	v_max3_f32 v144, v144, v64, v65
	v_max3_f32 v144, v144, v66, v67
	v_max3_f32 v144, v144, v68, v69
	v_max3_f32 v144, v144, v70, v71
	v_max3_f32 v144, v144, v72, v73
	v_max3_f32 v144, v144, v74, v75
	v_max3_f32 v144, v144, v76, v77
	s_waitcnt lgkmcnt(2)
	v_mfma_f32_32x32x16_bf16 v[16:31], v[152:155], v[230:233], v[16:31]
	v_max3_f32 v144, v144, v78, v79
	v_mov_b32_e32 v145, v144
	s_nop 1
	v_permlane32_swap_b32_e32 v144, v145
	v_max_f32_e32 v145, v145, v145
	v_max_f32_e32 v144, v144, v144
	v_max_f32_e32 v144, v144, v145
	v_sub_f32_e32 v145, v144, v200
	v_cmp_ge_f32_e32 vcc, s49, v145
	v_max_f32_e32 v145, v200, v200
	v_max_f32_e32 v145, v145, v144
	s_waitcnt lgkmcnt(0)
	v_mfma_f32_32x32x16_bf16 v[16:31], v[156:159], v[234:237], v[16:31]
	v_sub_f32_e32 v144, v200, v145
	v_mul_f32_e32 v144, 0x3e38aa3b, v144
	v_exp_f32_e32 v144, v144
	s_cmp_eq_u64 vcc, exec
	s_cselect_b64 s[0:1], -1, 0
	s_waitcnt vmcnt(4)
	v_cndmask_b32_e64 v144, v144, 1.0, s[0:1]
	v_cmp_gt_f32_e32 vcc, 1.0, v144
	ds_write_b128 v171, v[136:139] offset:49152
	ds_write_b128 v172, v[140:143] offset:49152
	s_cbranch_vccz .LBB0_693
	s_and_saveexec_b64 s[38:39], s[6:7]
	ds_write_b32 v166, v144 offset:128
	s_or_b64 exec, exec, s[38:39]
	s_waitcnt lgkmcnt(0)
	v_add_u32_e32 v140, v161, v178
	ds_read_b128 v[128:131], v140 offset:224
	ds_read_b128 v[132:135], v140 offset:192
	ds_read_b128 v[136:139], v140 offset:160
	ds_read_b128 v[140:143], v140 offset:128
	s_waitcnt lgkmcnt(3)
	v_pk_mul_f32 v[12:13], v[12:13], v[128:129]
	s_waitcnt lgkmcnt(2)
	v_pk_mul_f32 v[8:9], v[8:9], v[132:133]
	s_waitcnt lgkmcnt(1)
	v_pk_mul_f32 v[4:5], v[4:5], v[136:137]
	v_pk_mul_f32 v[14:15], v[14:15], v[130:131]
	v_pk_mul_f32 v[10:11], v[10:11], v[134:135]
	v_pk_mul_f32 v[6:7], v[6:7], v[138:139]
	s_waitcnt lgkmcnt(0)
	v_pk_mul_f32 v[2:3], v[2:3], v[142:143]
	v_pk_mul_f32 v[0:1], v[0:1], v[140:141]
	v_pk_mul_f32 v[60:61], v[60:61], v[128:129]
	v_pk_mul_f32 v[56:57], v[56:57], v[132:133]
	v_pk_mul_f32 v[52:53], v[52:53], v[136:137]
	v_pk_mul_f32 v[62:63], v[62:63], v[130:131]
	v_pk_mul_f32 v[58:59], v[58:59], v[134:135]
	v_pk_mul_f32 v[54:55], v[54:55], v[138:139]
	v_pk_mul_f32 v[50:51], v[50:51], v[142:143]
	v_pk_mul_f32 v[48:49], v[48:49], v[140:141]
	v_pk_mul_f32 v[44:45], v[44:45], v[128:129]
	v_pk_mul_f32 v[40:41], v[40:41], v[132:133]
	v_pk_mul_f32 v[36:37], v[36:37], v[136:137]
	v_pk_mul_f32 v[46:47], v[46:47], v[130:131]
	v_pk_mul_f32 v[42:43], v[42:43], v[134:135]
	v_pk_mul_f32 v[38:39], v[38:39], v[138:139]
	v_pk_mul_f32 v[34:35], v[34:35], v[142:143]
	v_pk_mul_f32 v[32:33], v[32:33], v[140:141]
	v_pk_mul_f32 v[28:29], v[28:29], v[128:129]
	v_pk_mul_f32 v[24:25], v[24:25], v[132:133]
	v_pk_mul_f32 v[20:21], v[20:21], v[136:137]
	v_pk_mul_f32 v[30:31], v[30:31], v[130:131]
	v_pk_mul_f32 v[26:27], v[26:27], v[134:135]
	v_pk_mul_f32 v[22:23], v[22:23], v[138:139]
	v_pk_mul_f32 v[18:19], v[18:19], v[142:143]
	v_pk_mul_f32 v[16:17], v[16:17], v[140:141]
.LBB0_693:
	v_cndmask_b32_e64 v148, v145, v200, s[0:1]
	v_mul_f32_e32 v128, 0xbe38aa3b, v148
	v_mov_b32_e32 v129, v128
	v_fmamk_f32 v80, v80, 0x3e38aa3b, v128
	v_fmamk_f32 v81, v81, 0x3e38aa3b, v128
	v_fmamk_f32 v82, v82, 0x3e38aa3b, v128
	v_fmamk_f32 v83, v83, 0x3e38aa3b, v128
	v_fmamk_f32 v84, v84, 0x3e38aa3b, v128
	v_fmamk_f32 v85, v85, 0x3e38aa3b, v128
	v_fmamk_f32 v86, v86, 0x3e38aa3b, v128
	v_fmamk_f32 v87, v87, 0x3e38aa3b, v128
	v_fmamk_f32 v88, v88, 0x3e38aa3b, v128
	v_fmamk_f32 v89, v89, 0x3e38aa3b, v128
	v_fmamk_f32 v90, v90, 0x3e38aa3b, v128
	v_fmamk_f32 v91, v91, 0x3e38aa3b, v128
	v_fmamk_f32 v92, v92, 0x3e38aa3b, v128
	v_fmamk_f32 v93, v93, 0x3e38aa3b, v128
	v_fmamk_f32 v94, v94, 0x3e38aa3b, v128
	v_fmac_f32_e32 v129, 0x3e38aa3b, v95
	v_exp_f32_e32 v145, v80
	v_exp_f32_e32 v158, v81
	v_exp_f32_e32 v146, v82
	v_exp_f32_e32 v159, v83
	v_exp_f32_e32 v147, v84
	v_exp_f32_e32 v200, v85
	v_exp_f32_e32 v157, v86
	v_exp_f32_e32 v203, v87
	v_exp_f32_e32 v149, v88
	v_exp_f32_e32 v153, v89
	v_exp_f32_e32 v150, v90
	v_exp_f32_e32 v154, v91
	v_exp_f32_e32 v151, v92
	v_exp_f32_e32 v155, v93
	v_exp_f32_e32 v152, v94
	v_exp_f32_e32 v156, v129
	v_pk_fma_f32 v[142:143], v[64:65], s[68:69], v[128:129] op_sel_hi:[1,0,0]
	v_add_f32_e32 v64, v189, v198
	v_fmac_f32_e32 v64, v188, v167
	v_add_f32_e32 v167, v201, v202
	v_pk_fma_f32 v[140:141], v[66:67], s[68:69], v[128:129] op_sel_hi:[1,0,0]
	v_pk_fma_f32 v[136:137], v[68:69], s[68:69], v[128:129] op_sel_hi:[1,0,0]
	v_pk_fma_f32 v[132:133], v[70:71], s[68:69], v[128:129] op_sel_hi:[1,0,0]
	v_pk_fma_f32 v[130:131], v[72:73], s[68:69], v[128:129] op_sel_hi:[1,0,0]
	v_pk_fma_f32 v[138:139], v[74:75], s[68:69], v[128:129] op_sel_hi:[1,0,0]
	v_pk_fma_f32 v[134:135], v[76:77], s[68:69], v[128:129] op_sel_hi:[1,0,0]
	v_pk_fma_f32 v[128:129], v[78:79], s[68:69], v[128:129] op_sel_hi:[1,0,0]
	v_fmac_f32_e32 v167, v64, v199
	s_add_i32 s91, s91, 2
	v_lshl_add_u64 v[162:163], v[162:163], 0, s[66:67]
	s_and_b64 vcc, exec, s[28:29]
	s_waitcnt lgkmcnt(0)
	s_barrier
	s_cbranch_vccnz .LBB0_695
	v_mov_b32_e32 v188, v144
	ds_write_b128 v173, v[240:243] offset:16384
	ds_write_b128 v174, v[244:247] offset:16384
	s_branch .LBB0_683

.LBB0_695:
	ds_write_b128 v173, v[240:243] offset:16384
	ds_write_b128 v174, v[244:247] offset:16384
	ds_read_b128 v[64:67], v170 offset:49152
	ds_read_b128 v[68:71], v170 offset:57344
	v_exp_f32_e32 v116, v138
	v_exp_f32_e32 v117, v139
	v_exp_f32_e32 v118, v134
	s_waitcnt lgkmcnt(1)
	v_mfma_f32_32x32x16_bf16 v[80:95], v[64:67], v[100:103], 0
	v_exp_f32_e32 v119, v135
	v_exp_f32_e32 v120, v128
	v_exp_f32_e32 v121, v129
	s_waitcnt lgkmcnt(0)
	v_mfma_f32_32x32x16_bf16 v[64:79], v[68:71], v[100:103], 0
	ds_read_b128 v[100:103], v186 offset:49152
	ds_read_b128 v[112:115], v186 offset:57344
	s_waitcnt lgkmcnt(1)
	v_mfma_f32_32x32x16_bf16 v[80:95], v[100:103], v[108:111], v[80:95]
	s_waitcnt lgkmcnt(0)
	v_mfma_f32_32x32x16_bf16 v[64:79], v[112:115], v[108:111], v[64:79]
	ds_read_b128 v[100:103], v175 offset:49152
	ds_read_b128 v[108:111], v175 offset:57344
	v_exp_f32_e32 v112, v132
	v_exp_f32_e32 v113, v133
	v_exp_f32_e32 v114, v130
	v_exp_f32_e32 v115, v131
	s_waitcnt lgkmcnt(1)
	v_mfma_f32_32x32x16_bf16 v[80:95], v[100:103], v[96:99], v[80:95]
	s_waitcnt lgkmcnt(0)
	v_mfma_f32_32x32x16_bf16 v[64:79], v[108:111], v[96:99], v[64:79]
	ds_read_b128 v[96:99], v187 offset:49152
	ds_read_b128 v[100:103], v187 offset:57344
	v_exp_f32_e32 v108, v140
	v_exp_f32_e32 v109, v141
	v_exp_f32_e32 v110, v136
	v_exp_f32_e32 v111, v137
	s_waitcnt lgkmcnt(1)
	v_mfma_f32_32x32x16_bf16 v[80:95], v[96:99], v[104:107], v[80:95]
	v_add_f32_e32 v96, 0, v145
	v_add_f32_e32 v96, v158, v96
	v_add_f32_e32 v96, v146, v96
	v_add_f32_e32 v96, v159, v96
	v_add_f32_e32 v96, v147, v96
	v_add_f32_e32 v96, v200, v96
	v_add_f32_e32 v96, v157, v96
	v_add_f32_e32 v96, v203, v96
	v_add_f32_e32 v96, v149, v96
	v_add_f32_e32 v96, v153, v96
	v_add_f32_e32 v96, v150, v96
	v_add_f32_e32 v96, v154, v96
	s_waitcnt lgkmcnt(0)
	v_mfma_f32_32x32x16_bf16 v[64:79], v[100:103], v[104:107], v[64:79]
	v_exp_f32_e32 v106, v142
	v_add_f32_e32 v96, v151, v96
	v_exp_f32_e32 v107, v143
	v_add_f32_e32 v96, v155, v96
	v_add_f32_e32 v96, v152, v96
	v_add_f32_e32 v96, v156, v96
	v_add_f32_e32 v96, v106, v96
	v_add_f32_e32 v96, v107, v96
	v_add_f32_e32 v96, v108, v96
	v_add_f32_e32 v96, v109, v96
	v_add_f32_e32 v96, v110, v96
	v_add_f32_e32 v96, v111, v96
	v_add_f32_e32 v96, v112, v96
	v_add_f32_e32 v96, v113, v96
	v_add_f32_e32 v96, v114, v96
	v_add_f32_e32 v96, v115, v96
	v_add_f32_e32 v96, v116, v96
	v_add_f32_e32 v96, v117, v96
	v_add_f32_e32 v96, v118, v96
	v_add_f32_e32 v96, v119, v96
	v_add_f32_e32 v96, v120, v96
	v_add_f32_e32 v96, v121, v96
	v_mov_b32_e32 v97, v96
	v_cvt_pk_bf16_f32 v98, v145, v158
	v_cvt_pk_bf16_f32 v99, v146, v159
	v_cvt_pk_bf16_f32 v100, v147, v200
	v_cvt_pk_bf16_f32 v101, v157, v203
	s_nop 1
	v_permlane32_swap_b32_e32 v96, v97
	v_permlane32_swap_b32_e32 v98, v100
	v_permlane32_swap_b32_e32 v99, v101
	v_cvt_pk_bf16_f32 v102, v149, v153
	v_cvt_pk_bf16_f32 v103, v150, v154
	v_cvt_pk_bf16_f32 v104, v151, v155
	v_cvt_pk_bf16_f32 v105, v152, v156
	v_cvt_pk_bf16_f32 v106, v106, v107
	v_cvt_pk_bf16_f32 v107, v108, v109
	v_cvt_pk_bf16_f32 v108, v110, v111
	v_cvt_pk_bf16_f32 v109, v112, v113
	v_cvt_pk_bf16_f32 v110, v114, v115
	v_cvt_pk_bf16_f32 v111, v116, v117
	v_cvt_pk_bf16_f32 v112, v118, v119
	v_cvt_pk_bf16_f32 v113, v120, v121
	s_nop 0
	v_permlane32_swap_b32_e32 v102, v104
	v_permlane32_swap_b32_e32 v103, v105
	v_permlane32_swap_b32_e32 v106, v108
	v_permlane32_swap_b32_e32 v107, v109
	v_permlane32_swap_b32_e32 v110, v112
	v_permlane32_swap_b32_e32 v111, v113
	ds_read_b64_tr_b16 v[114:115], v169 offset:0
	ds_read_b64_tr_b16 v[116:117], v169 offset:0x800
	ds_read_b64_tr_b16 v[118:119], v169 offset:0x1000
	ds_read_b64_tr_b16 v[120:121], v169 offset:0x1800
	ds_read_b64_tr_b16 v[122:123], v169 offset:0x2000
	ds_read_b64_tr_b16 v[124:125], v169 offset:0x2800
	ds_read_b64_tr_b16 v[126:127], v169 offset:0x3000
	ds_read_b64_tr_b16 v[128:129], v169 offset:0x3800
	s_nop 0
	s_waitcnt lgkmcnt(6)
	v_mfma_f32_32x32x16_bf16 v[0:15], v[98:101], v[114:117], v[0:15]
	ds_read_b64_tr_b16 v[114:115], v169 offset:0x200
	ds_read_b64_tr_b16 v[116:117], v169 offset:0xa00
	s_waitcnt lgkmcnt(6)
	v_mfma_f32_32x32x16_bf16 v[0:15], v[102:105], v[118:121], v[0:15]
	ds_read_b64_tr_b16 v[118:119], v169 offset:0x1200
	ds_read_b64_tr_b16 v[120:121], v169 offset:0x1a00
	s_waitcnt lgkmcnt(6)
	v_mfma_f32_32x32x16_bf16 v[0:15], v[106:109], v[122:125], v[0:15]
	ds_read_b64_tr_b16 v[122:123], v169 offset:0x2200
	ds_read_b64_tr_b16 v[124:125], v169 offset:0x2a00
	s_waitcnt lgkmcnt(6)
	v_mfma_f32_32x32x16_bf16 v[0:15], v[110:113], v[126:129], v[0:15]
	ds_read_b64_tr_b16 v[126:127], v169 offset:0x3200
	ds_read_b64_tr_b16 v[128:129], v169 offset:0x3a00
	s_waitcnt lgkmcnt(6)
	v_mfma_f32_32x32x16_bf16 v[48:63], v[98:101], v[114:117], v[48:63]
	ds_read_b64_tr_b16 v[114:115], v169 offset:0x400
	ds_read_b64_tr_b16 v[116:117], v169 offset:0xc00
	s_waitcnt lgkmcnt(6)
	v_mfma_f32_32x32x16_bf16 v[48:63], v[102:105], v[118:121], v[48:63]
	ds_read_b64_tr_b16 v[118:119], v169 offset:0x1400
	ds_read_b64_tr_b16 v[120:121], v169 offset:0x1c00
	s_waitcnt lgkmcnt(6)
	v_mfma_f32_32x32x16_bf16 v[48:63], v[106:109], v[122:125], v[48:63]
	ds_read_b64_tr_b16 v[122:123], v169 offset:0x2400
	ds_read_b64_tr_b16 v[124:125], v169 offset:0x2c00
	s_waitcnt lgkmcnt(6)
	v_mfma_f32_32x32x16_bf16 v[48:63], v[110:113], v[126:129], v[48:63]
	ds_read_b64_tr_b16 v[126:127], v169 offset:0x3400
	ds_read_b64_tr_b16 v[128:129], v169 offset:0x3c00
	s_waitcnt lgkmcnt(6)
	v_mfma_f32_32x32x16_bf16 v[32:47], v[98:101], v[114:117], v[32:47]
	ds_read_b64_tr_b16 v[114:115], v169 offset:0x600
	ds_read_b64_tr_b16 v[116:117], v169 offset:0xe00
	s_waitcnt lgkmcnt(6)
	v_mfma_f32_32x32x16_bf16 v[32:47], v[102:105], v[118:121], v[32:47]
	ds_read_b64_tr_b16 v[118:119], v169 offset:0x1600
	ds_read_b64_tr_b16 v[120:121], v169 offset:0x1e00
	s_waitcnt lgkmcnt(6)
	v_mfma_f32_32x32x16_bf16 v[32:47], v[106:109], v[122:125], v[32:47]
	ds_read_b64_tr_b16 v[122:123], v169 offset:0x2600
	ds_read_b64_tr_b16 v[124:125], v169 offset:0x2e00
	s_waitcnt lgkmcnt(6)
	v_mfma_f32_32x32x16_bf16 v[32:47], v[110:113], v[126:129], v[32:47]
	ds_read_b64_tr_b16 v[126:127], v169 offset:0x3600
	ds_read_b64_tr_b16 v[128:129], v169 offset:0x3e00
	s_waitcnt lgkmcnt(6)
	v_mfma_f32_32x32x16_bf16 v[16:31], v[98:101], v[114:117], v[16:31]
	v_max_f32_e32 v98, v81, v81
	v_max_f32_e32 v99, v80, v80
	v_max_f32_e32 v98, v99, v98
	v_max3_f32 v98, v98, v82, v83
	v_max3_f32 v98, v98, v84, v85
	v_max3_f32 v98, v98, v86, v87
	v_max3_f32 v98, v98, v88, v89
	v_max3_f32 v98, v98, v90, v91
	v_max3_f32 v98, v98, v92, v93
	s_waitcnt lgkmcnt(4)
	v_mfma_f32_32x32x16_bf16 v[16:31], v[102:105], v[118:121], v[16:31]
	v_max3_f32 v98, v98, v94, v95
	v_max3_f32 v98, v98, v64, v65
	v_max3_f32 v98, v98, v66, v67
	v_max3_f32 v98, v98, v68, v69
	v_max3_f32 v98, v98, v70, v71
	v_max3_f32 v98, v98, v72, v73
	v_max3_f32 v98, v98, v74, v75
	v_max3_f32 v98, v98, v76, v77
	s_waitcnt lgkmcnt(2)
	v_mfma_f32_32x32x16_bf16 v[16:31], v[106:109], v[122:125], v[16:31]
	v_max3_f32 v98, v98, v78, v79
	v_mov_b32_e32 v99, v98
	s_nop 1
	v_permlane32_swap_b32_e32 v98, v99
	v_max_f32_e32 v99, v99, v99
	v_max_f32_e32 v98, v98, v98
	v_max_f32_e32 v98, v98, v99
	v_sub_f32_e32 v99, v98, v148
	v_cmp_ge_f32_e32 vcc, s49, v99
	v_max_f32_e32 v99, v148, v148
	v_max_f32_e32 v99, v99, v98
	s_waitcnt lgkmcnt(0)
	v_mfma_f32_32x32x16_bf16 v[16:31], v[110:113], v[126:129], v[16:31]
	v_sub_f32_e32 v98, v148, v99
	v_mul_f32_e32 v98, 0x3e38aa3b, v98
	v_exp_f32_e32 v98, v98
	s_cmp_eq_u64 vcc, exec
	s_cselect_b64 s[0:1], -1, 0
	v_cndmask_b32_e64 v98, v98, 1.0, s[0:1]
	v_cmp_gt_f32_e32 vcc, 1.0, v98
	s_barrier
	s_cbranch_vccz .LBB0_699
	s_and_saveexec_b64 s[28:29], s[6:7]
	s_movk_i32 s91, 0x2a00
	ds_write_b32 v166, v98 offset:128
	s_or_b64 exec, exec, s[28:29]
	s_waitcnt lgkmcnt(0)
	v_add_u32_e32 v112, v161, v178
	ds_read_b128 v[100:103], v112 offset:224
	ds_read_b128 v[104:107], v112 offset:192
	ds_read_b128 v[108:111], v112 offset:160
	ds_read_b128 v[112:115], v112 offset:128
	s_waitcnt lgkmcnt(3)
	v_pk_mul_f32 v[12:13], v[12:13], v[100:101]
	s_waitcnt lgkmcnt(2)
	v_pk_mul_f32 v[8:9], v[8:9], v[104:105]
	s_waitcnt lgkmcnt(1)
	v_pk_mul_f32 v[4:5], v[4:5], v[108:109]
	v_pk_mul_f32 v[14:15], v[14:15], v[102:103]
	v_pk_mul_f32 v[10:11], v[10:11], v[106:107]
	v_pk_mul_f32 v[6:7], v[6:7], v[110:111]
	s_waitcnt lgkmcnt(0)
	v_pk_mul_f32 v[2:3], v[2:3], v[114:115]
	v_pk_mul_f32 v[0:1], v[0:1], v[112:113]
	v_pk_mul_f32 v[60:61], v[60:61], v[100:101]
	v_pk_mul_f32 v[56:57], v[56:57], v[104:105]
	v_pk_mul_f32 v[52:53], v[52:53], v[108:109]
	v_pk_mul_f32 v[62:63], v[62:63], v[102:103]
	v_pk_mul_f32 v[58:59], v[58:59], v[106:107]
	v_pk_mul_f32 v[54:55], v[54:55], v[110:111]
	v_pk_mul_f32 v[50:51], v[50:51], v[114:115]
	v_pk_mul_f32 v[48:49], v[48:49], v[112:113]
	v_pk_mul_f32 v[44:45], v[44:45], v[100:101]
	v_pk_mul_f32 v[40:41], v[40:41], v[104:105]
	v_pk_mul_f32 v[36:37], v[36:37], v[108:109]
	v_pk_mul_f32 v[46:47], v[46:47], v[102:103]
	v_pk_mul_f32 v[42:43], v[42:43], v[106:107]
	v_pk_mul_f32 v[38:39], v[38:39], v[110:111]
	v_pk_mul_f32 v[34:35], v[34:35], v[114:115]
	v_pk_mul_f32 v[32:33], v[32:33], v[112:113]
	v_pk_mul_f32 v[28:29], v[28:29], v[100:101]
	v_pk_mul_f32 v[24:25], v[24:25], v[104:105]
	v_pk_mul_f32 v[20:21], v[20:21], v[108:109]
	v_pk_mul_f32 v[30:31], v[30:31], v[102:103]
	v_pk_mul_f32 v[26:27], v[26:27], v[106:107]
	v_pk_mul_f32 v[22:23], v[22:23], v[110:111]
	v_pk_mul_f32 v[18:19], v[18:19], v[114:115]
	v_pk_mul_f32 v[16:17], v[16:17], v[112:113]
	s_branch .LBB0_700

.LBB0_707:
	ds_read_b128 v[64:67], v170 offset:49152
	ds_read_b128 v[68:71], v170 offset:57344
	v_add_f32_e32 v144, 0, v145
	v_add_f32_e32 v144, v158, v144
	v_add_f32_e32 v144, v146, v144
	s_waitcnt lgkmcnt(1)
	v_mfma_f32_32x32x16_bf16 v[80:95], v[64:67], v[100:103], 0
	v_add_f32_e32 v144, v159, v144
	v_add_f32_e32 v144, v147, v144
	ds_read_b128 v[204:207], v186 offset:49152
	ds_read_b128 v[226:229], v186 offset:57344
	v_add_f32_e32 v144, v200, v144
	v_add_f32_e32 v144, v157, v144
	v_add_f32_e32 v144, v203, v144
	v_add_f32_e32 v144, v149, v144
	s_waitcnt lgkmcnt(2)
	v_mfma_f32_32x32x16_bf16 v[64:79], v[68:71], v[100:103], 0
	v_add_f32_e32 v144, v153, v144
	v_add_f32_e32 v144, v150, v144
	v_add_f32_e32 v144, v154, v144
	v_exp_f32_e32 v142, v142
	v_add_f32_e32 v144, v151, v144
	v_exp_f32_e32 v143, v143
	v_add_f32_e32 v144, v155, v144
	s_waitcnt lgkmcnt(1)
	v_mfma_f32_32x32x16_bf16 v[80:95], v[204:207], v[108:111], v[80:95]
	v_exp_f32_e32 v140, v140
	v_add_f32_e32 v144, v152, v144
	v_exp_f32_e32 v141, v141
	v_add_f32_e32 v144, v156, v144
	v_exp_f32_e32 v136, v136
	v_add_f32_e32 v144, v142, v144
	v_exp_f32_e32 v137, v137
	s_waitcnt lgkmcnt(0)
	v_mfma_f32_32x32x16_bf16 v[64:79], v[226:229], v[108:111], v[64:79]
	ds_read_b128 v[204:207], v175 offset:49152
	ds_read_b128 v[226:229], v175 offset:57344
	v_add_f32_e32 v144, v143, v144
	v_exp_f32_e32 v132, v132
	v_add_f32_e32 v144, v140, v144
	v_exp_f32_e32 v133, v133
	v_add_f32_e32 v144, v141, v144
	v_exp_f32_e32 v130, v130
	s_waitcnt lgkmcnt(1)
	v_mfma_f32_32x32x16_bf16 v[80:95], v[204:207], v[96:99], v[80:95]
	v_add_f32_e32 v144, v136, v144
	v_exp_f32_e32 v131, v131
	v_add_f32_e32 v144, v137, v144
	v_exp_f32_e32 v138, v138
	v_add_f32_e32 v144, v132, v144
	v_exp_f32_e32 v139, v139
	v_add_f32_e32 v144, v133, v144
	s_waitcnt lgkmcnt(0)
	v_mfma_f32_32x32x16_bf16 v[64:79], v[226:229], v[96:99], v[64:79]
	ds_read_b128 v[204:207], v187 offset:49152
	ds_read_b128 v[226:229], v187 offset:57344
	v_exp_f32_e32 v134, v134
	v_add_f32_e32 v144, v130, v144
	v_exp_f32_e32 v135, v135
	v_add_f32_e32 v144, v131, v144
	v_exp_f32_e32 v128, v128
	v_add_f32_e32 v144, v138, v144
	s_waitcnt lgkmcnt(1)
	v_mfma_f32_32x32x16_bf16 v[80:95], v[204:207], v[104:107], v[80:95]
	v_exp_f32_e32 v129, v129
	v_add_f32_e32 v144, v139, v144
	v_add_f32_e32 v144, v134, v144
	v_add_f32_e32 v144, v135, v144
	v_add_f32_e32 v144, v128, v144
	v_add_f32_e32 v189, v129, v144
	v_mov_b32_e32 v198, v189
	s_waitcnt lgkmcnt(0)
	v_mfma_f32_32x32x16_bf16 v[64:79], v[226:229], v[104:107], v[64:79]
	v_cvt_pk_bf16_f32 v144, v145, v158
	v_cvt_pk_bf16_f32 v145, v146, v159
	v_cvt_pk_bf16_f32 v146, v147, v200
	v_permlane32_swap_b32_e32 v189, v198
	v_cvt_pk_bf16_f32 v147, v157, v203
	v_permlane32_swap_b32_e32 v144, v146
	v_cvt_pk_bf16_f32 v200, v149, v153
	v_cvt_pk_bf16_f32 v201, v150, v154
	v_cvt_pk_bf16_f32 v202, v151, v155
	v_cvt_pk_bf16_f32 v203, v152, v156
	v_cvt_pk_bf16_f32 v150, v142, v143
	v_cvt_pk_bf16_f32 v151, v140, v141
	v_cvt_pk_bf16_f32 v152, v136, v137
	v_cvt_pk_bf16_f32 v153, v132, v133
	v_cvt_pk_bf16_f32 v154, v130, v131
	v_cvt_pk_bf16_f32 v155, v138, v139
	v_cvt_pk_bf16_f32 v156, v134, v135
	v_cvt_pk_bf16_f32 v157, v128, v129
	v_permlane32_swap_b32_e32 v145, v147
	v_permlane32_swap_b32_e32 v200, v202
	v_permlane32_swap_b32_e32 v201, v203
	v_permlane32_swap_b32_e32 v150, v152
	v_permlane32_swap_b32_e32 v151, v153
	v_permlane32_swap_b32_e32 v154, v156
	v_permlane32_swap_b32_e32 v155, v157
	v_add_co_u32_e32 v128, vcc, s33, v162
	s_nop 1
	v_addc_co_u32_e32 v129, vcc, -1, v163, vcc
	v_add_co_u32_e32 v132, vcc, s70, v162
	s_nop 1
	v_addc_co_u32_e32 v133, vcc, -1, v163, vcc
	v_add_co_u32_e32 v136, vcc, s71, v162
	global_load_dwordx4 v[240:243], v[128:129], off
	s_nop 0
	global_load_dwordx4 v[244:247], v[132:133], off
	v_addc_co_u32_e32 v137, vcc, -1, v163, vcc
	v_add_co_u32_e32 v140, vcc, s72, v162
	s_nop 1
	v_addc_co_u32_e32 v141, vcc, -1, v163, vcc
	global_load_dwordx4 v[136:139], v[136:137], off
	s_nop 0
	global_load_dwordx4 v[140:143], v[140:141], off
	ds_read_b64_tr_b16 v[204:205], v169 offset:0
	ds_read_b64_tr_b16 v[206:207], v169 offset:0x800
	ds_read_b64_tr_b16 v[226:227], v169 offset:0x1000
	ds_read_b64_tr_b16 v[228:229], v169 offset:0x1800
	ds_read_b64_tr_b16 v[230:231], v169 offset:0x2000
	ds_read_b64_tr_b16 v[232:233], v169 offset:0x2800
	ds_read_b64_tr_b16 v[234:235], v169 offset:0x3000
	ds_read_b64_tr_b16 v[236:237], v169 offset:0x3800
	s_nop 0
	s_waitcnt lgkmcnt(6)
	v_mfma_f32_32x32x16_bf16 v[32:47], v[144:147], v[204:207], v[32:47]
	ds_read_b64_tr_b16 v[204:205], v169 offset:0x200
	ds_read_b64_tr_b16 v[206:207], v169 offset:0xa00
	s_waitcnt lgkmcnt(6)
	v_mfma_f32_32x32x16_bf16 v[32:47], v[200:203], v[226:229], v[32:47]
	ds_read_b64_tr_b16 v[226:227], v169 offset:0x1200
	ds_read_b64_tr_b16 v[228:229], v169 offset:0x1a00
	s_waitcnt lgkmcnt(6)
	v_mfma_f32_32x32x16_bf16 v[32:47], v[150:153], v[230:233], v[32:47]
	ds_read_b64_tr_b16 v[230:231], v169 offset:0x2200
	ds_read_b64_tr_b16 v[232:233], v169 offset:0x2a00
	s_waitcnt lgkmcnt(6)
	v_mfma_f32_32x32x16_bf16 v[32:47], v[154:157], v[234:237], v[32:47]
	ds_read_b64_tr_b16 v[234:235], v169 offset:0x3200
	ds_read_b64_tr_b16 v[236:237], v169 offset:0x3a00
	s_waitcnt lgkmcnt(6)
	v_mfma_f32_32x32x16_bf16 v[48:63], v[144:147], v[204:207], v[48:63]
	ds_read_b64_tr_b16 v[204:205], v169 offset:0x400
	ds_read_b64_tr_b16 v[206:207], v169 offset:0xc00
	s_waitcnt lgkmcnt(6)
	v_mfma_f32_32x32x16_bf16 v[48:63], v[200:203], v[226:229], v[48:63]
	ds_read_b64_tr_b16 v[226:227], v169 offset:0x1400
	ds_read_b64_tr_b16 v[228:229], v169 offset:0x1c00
	s_waitcnt lgkmcnt(6)
	v_mfma_f32_32x32x16_bf16 v[48:63], v[150:153], v[230:233], v[48:63]
	ds_read_b64_tr_b16 v[230:231], v169 offset:0x2400
	ds_read_b64_tr_b16 v[232:233], v169 offset:0x2c00
	s_waitcnt lgkmcnt(6)
	v_mfma_f32_32x32x16_bf16 v[48:63], v[154:157], v[234:237], v[48:63]
	ds_read_b64_tr_b16 v[234:235], v169 offset:0x3400
	ds_read_b64_tr_b16 v[236:237], v169 offset:0x3c00
	s_waitcnt lgkmcnt(6)
	v_mfma_f32_32x32x16_bf16 v[16:31], v[144:147], v[204:207], v[16:31]
	ds_read_b64_tr_b16 v[204:205], v169 offset:0x600
	ds_read_b64_tr_b16 v[206:207], v169 offset:0xe00
	s_waitcnt lgkmcnt(6)
	v_mfma_f32_32x32x16_bf16 v[16:31], v[200:203], v[226:229], v[16:31]
	ds_read_b64_tr_b16 v[226:227], v169 offset:0x1600
	ds_read_b64_tr_b16 v[228:229], v169 offset:0x1e00
	s_waitcnt lgkmcnt(6)
	v_mfma_f32_32x32x16_bf16 v[16:31], v[150:153], v[230:233], v[16:31]
	ds_read_b64_tr_b16 v[230:231], v169 offset:0x2600
	ds_read_b64_tr_b16 v[232:233], v169 offset:0x2e00
	s_waitcnt lgkmcnt(6)
	v_mfma_f32_32x32x16_bf16 v[16:31], v[154:157], v[234:237], v[16:31]
	ds_read_b64_tr_b16 v[234:235], v169 offset:0x3600
	ds_read_b64_tr_b16 v[236:237], v169 offset:0x3e00
	s_waitcnt lgkmcnt(6)
	v_mfma_f32_32x32x16_bf16 v[0:15], v[144:147], v[204:207], v[0:15]
	v_max_f32_e32 v144, v81, v81
	v_max_f32_e32 v145, v80, v80
	v_max_f32_e32 v144, v145, v144
	v_max3_f32 v144, v144, v82, v83
	v_max3_f32 v144, v144, v84, v85
	v_max3_f32 v144, v144, v86, v87
	v_max3_f32 v144, v144, v88, v89
	v_max3_f32 v144, v144, v90, v91
	v_max3_f32 v144, v144, v92, v93
	s_waitcnt lgkmcnt(4)
	v_mfma_f32_32x32x16_bf16 v[0:15], v[200:203], v[226:229], v[0:15]
	v_max3_f32 v144, v144, v94, v95
	v_max3_f32 v144, v144, v64, v65
	v_max3_f32 v144, v144, v66, v67
	v_max3_f32 v144, v144, v68, v69
	v_max3_f32 v144, v144, v70, v71
	v_max3_f32 v144, v144, v72, v73
	v_max3_f32 v144, v144, v74, v75
	v_max3_f32 v144, v144, v76, v77
	s_waitcnt lgkmcnt(2)
	v_mfma_f32_32x32x16_bf16 v[0:15], v[150:153], v[230:233], v[0:15]
	v_max3_f32 v144, v144, v78, v79
	v_mov_b32_e32 v145, v144
	s_nop 1
	v_permlane32_swap_b32_e32 v144, v145
	v_max_f32_e32 v145, v145, v145
	v_max_f32_e32 v144, v144, v144
	v_max_f32_e32 v144, v144, v145
	v_sub_f32_e32 v145, v144, v148
	v_cmp_ge_f32_e32 vcc, s26, v145
	v_max_f32_e32 v145, v148, v148
	v_max_f32_e32 v144, v145, v144
	s_waitcnt lgkmcnt(0)
	v_mfma_f32_32x32x16_bf16 v[0:15], v[154:157], v[234:237], v[0:15]
	v_sub_f32_e32 v145, v148, v144
	v_mul_f32_e32 v145, 0x3e38aa3b, v145
	v_exp_f32_e32 v145, v145
	s_cmp_eq_u64 vcc, exec
	s_cselect_b64 s[0:1], -1, 0
	s_waitcnt vmcnt(4)
	v_cndmask_b32_e64 v199, v145, 1.0, s[0:1]
	v_cmp_gt_f32_e32 vcc, 1.0, v199
	s_waitcnt vmcnt(7)
	s_waitcnt vmcnt(6)
	s_waitcnt vmcnt(5)
	ds_write_b128 v171, v[116:119] offset:32768
	s_waitcnt vmcnt(4)
	ds_write_b128 v172, v[124:127] offset:32768
	s_cbranch_vccz .LBB0_711
	s_and_saveexec_b64 s[20:21], s[6:7]
	ds_write_b32 v166, v199 offset:128
	s_or_b64 exec, exec, s[20:21]
	s_waitcnt lgkmcnt(0)
	v_add_u32_e32 v145, v161, v178
	ds_read_b128 v[150:153], v145 offset:224
	ds_read_b128 v[154:157], v145 offset:192
	ds_read_b128 v[200:203], v145 offset:160
	ds_read_b128 v[204:207], v145 offset:128
	s_waitcnt lgkmcnt(3)
	v_pk_mul_f32 v[44:45], v[44:45], v[150:151]
	s_waitcnt lgkmcnt(2)
	v_pk_mul_f32 v[40:41], v[40:41], v[154:155]
	s_waitcnt lgkmcnt(1)
	v_pk_mul_f32 v[36:37], v[36:37], v[200:201]
	v_pk_mul_f32 v[46:47], v[46:47], v[152:153]
	v_pk_mul_f32 v[42:43], v[42:43], v[156:157]
	v_pk_mul_f32 v[38:39], v[38:39], v[202:203]
	s_waitcnt lgkmcnt(0)
	v_pk_mul_f32 v[34:35], v[34:35], v[206:207]
	v_pk_mul_f32 v[32:33], v[32:33], v[204:205]
	v_pk_mul_f32 v[60:61], v[60:61], v[150:151]
	v_pk_mul_f32 v[56:57], v[56:57], v[154:155]
	v_pk_mul_f32 v[52:53], v[52:53], v[200:201]
	v_pk_mul_f32 v[62:63], v[62:63], v[152:153]
	v_pk_mul_f32 v[58:59], v[58:59], v[156:157]
	v_pk_mul_f32 v[54:55], v[54:55], v[202:203]
	v_pk_mul_f32 v[50:51], v[50:51], v[206:207]
	v_pk_mul_f32 v[48:49], v[48:49], v[204:205]
	v_pk_mul_f32 v[28:29], v[28:29], v[150:151]
	v_pk_mul_f32 v[24:25], v[24:25], v[154:155]
	v_pk_mul_f32 v[20:21], v[20:21], v[200:201]
	v_pk_mul_f32 v[30:31], v[30:31], v[152:153]
	v_pk_mul_f32 v[26:27], v[26:27], v[156:157]
	v_pk_mul_f32 v[22:23], v[22:23], v[202:203]
	v_pk_mul_f32 v[18:19], v[18:19], v[206:207]
	v_pk_mul_f32 v[16:17], v[16:17], v[204:205]
	v_pk_mul_f32 v[12:13], v[12:13], v[150:151]
	v_pk_mul_f32 v[8:9], v[8:9], v[154:155]
	v_pk_mul_f32 v[4:5], v[4:5], v[200:201]
	v_pk_mul_f32 v[14:15], v[14:15], v[152:153]
	v_pk_mul_f32 v[10:11], v[10:11], v[156:157]
	v_pk_mul_f32 v[6:7], v[6:7], v[202:203]
	v_pk_mul_f32 v[2:3], v[2:3], v[206:207]
	v_pk_mul_f32 v[0:1], v[0:1], v[204:205]

.LBB0_713:
	s_waitcnt lgkmcnt(0)
	ds_read_b64_tr_b16 v[204:205], v168 offset:0
	ds_read_b64_tr_b16 v[206:207], v168 offset:0x800
	ds_read_b64_tr_b16 v[226:227], v168 offset:0x1000
	ds_read_b64_tr_b16 v[228:229], v168 offset:0x1800
	ds_read_b64_tr_b16 v[230:231], v168 offset:0x2000
	ds_read_b64_tr_b16 v[232:233], v168 offset:0x2800
	ds_read_b64_tr_b16 v[234:235], v168 offset:0x3000
	ds_read_b64_tr_b16 v[236:237], v168 offset:0x3800
	s_nop 0
	s_waitcnt lgkmcnt(6)
	v_mfma_f32_32x32x16_bf16 v[32:47], v[144:147], v[204:207], v[32:47]
	ds_read_b64_tr_b16 v[204:205], v168 offset:0x200
	ds_read_b64_tr_b16 v[206:207], v168 offset:0xa00
	s_waitcnt lgkmcnt(6)
	v_mfma_f32_32x32x16_bf16 v[32:47], v[148:151], v[226:229], v[32:47]
	ds_read_b64_tr_b16 v[226:227], v168 offset:0x1200
	ds_read_b64_tr_b16 v[228:229], v168 offset:0x1a00
	s_waitcnt lgkmcnt(6)
	v_mfma_f32_32x32x16_bf16 v[32:47], v[152:155], v[230:233], v[32:47]
	ds_read_b64_tr_b16 v[230:231], v168 offset:0x2200
	ds_read_b64_tr_b16 v[232:233], v168 offset:0x2a00
	s_waitcnt lgkmcnt(6)
	v_mfma_f32_32x32x16_bf16 v[32:47], v[156:159], v[234:237], v[32:47]
	ds_read_b64_tr_b16 v[234:235], v168 offset:0x3200
	ds_read_b64_tr_b16 v[236:237], v168 offset:0x3a00
	s_waitcnt lgkmcnt(6)
	v_mfma_f32_32x32x16_bf16 v[48:63], v[144:147], v[204:207], v[48:63]
	ds_read_b64_tr_b16 v[204:205], v168 offset:0x400
	ds_read_b64_tr_b16 v[206:207], v168 offset:0xc00
	s_waitcnt lgkmcnt(6)
	v_mfma_f32_32x32x16_bf16 v[48:63], v[148:151], v[226:229], v[48:63]
	ds_read_b64_tr_b16 v[226:227], v168 offset:0x1400
	ds_read_b64_tr_b16 v[228:229], v168 offset:0x1c00
	s_waitcnt lgkmcnt(6)
	v_mfma_f32_32x32x16_bf16 v[48:63], v[152:155], v[230:233], v[48:63]
	ds_read_b64_tr_b16 v[230:231], v168 offset:0x2400
	ds_read_b64_tr_b16 v[232:233], v168 offset:0x2c00
	s_waitcnt lgkmcnt(6)
	v_mfma_f32_32x32x16_bf16 v[48:63], v[156:159], v[234:237], v[48:63]
	ds_read_b64_tr_b16 v[234:235], v168 offset:0x3400
	ds_read_b64_tr_b16 v[236:237], v168 offset:0x3c00
	s_waitcnt lgkmcnt(6)
	v_mfma_f32_32x32x16_bf16 v[16:31], v[144:147], v[204:207], v[16:31]
	ds_read_b64_tr_b16 v[204:205], v168 offset:0x600
	ds_read_b64_tr_b16 v[206:207], v168 offset:0xe00
	s_waitcnt lgkmcnt(6)
	v_mfma_f32_32x32x16_bf16 v[16:31], v[148:151], v[226:229], v[16:31]
	ds_read_b64_tr_b16 v[226:227], v168 offset:0x1600
	ds_read_b64_tr_b16 v[228:229], v168 offset:0x1e00
	s_waitcnt lgkmcnt(6)
	v_mfma_f32_32x32x16_bf16 v[16:31], v[152:155], v[230:233], v[16:31]
	ds_read_b64_tr_b16 v[230:231], v168 offset:0x2600
	ds_read_b64_tr_b16 v[232:233], v168 offset:0x2e00
	s_waitcnt lgkmcnt(6)
	v_mfma_f32_32x32x16_bf16 v[16:31], v[156:159], v[234:237], v[16:31]
	ds_read_b64_tr_b16 v[234:235], v168 offset:0x3600
	ds_read_b64_tr_b16 v[236:237], v168 offset:0x3e00
	s_waitcnt lgkmcnt(6)
	v_mfma_f32_32x32x16_bf16 v[0:15], v[144:147], v[204:207], v[0:15]
	v_max_f32_e32 v144, v81, v81
	v_max_f32_e32 v145, v80, v80
	v_max_f32_e32 v144, v145, v144
	v_max3_f32 v144, v144, v82, v83
	v_max3_f32 v144, v144, v84, v85
	v_max3_f32 v144, v144, v86, v87
	v_max3_f32 v144, v144, v88, v89
	v_max3_f32 v144, v144, v90, v91
	v_max3_f32 v144, v144, v92, v93
	s_waitcnt lgkmcnt(4)
	v_mfma_f32_32x32x16_bf16 v[0:15], v[148:151], v[226:229], v[0:15]
	v_max3_f32 v144, v144, v94, v95
	v_max3_f32 v144, v144, v64, v65
	v_max3_f32 v144, v144, v66, v67
	v_max3_f32 v144, v144, v68, v69
	v_max3_f32 v144, v144, v70, v71
	v_max3_f32 v144, v144, v72, v73
	v_max3_f32 v144, v144, v74, v75
	v_max3_f32 v144, v144, v76, v77
	s_waitcnt lgkmcnt(2)
	v_mfma_f32_32x32x16_bf16 v[0:15], v[152:155], v[230:233], v[0:15]
	v_max3_f32 v144, v144, v78, v79
	v_mov_b32_e32 v145, v144
	s_nop 1
	v_permlane32_swap_b32_e32 v144, v145
	v_max_f32_e32 v145, v145, v145
	v_max_f32_e32 v144, v144, v144
	v_max_f32_e32 v144, v144, v145
	v_sub_f32_e32 v145, v144, v200
	v_cmp_ge_f32_e32 vcc, s26, v145
	v_max_f32_e32 v145, v200, v200
	v_max_f32_e32 v145, v145, v144
	s_waitcnt lgkmcnt(0)
	v_mfma_f32_32x32x16_bf16 v[0:15], v[156:159], v[234:237], v[0:15]
	v_sub_f32_e32 v144, v200, v145
	v_mul_f32_e32 v144, 0x3e38aa3b, v144
	v_exp_f32_e32 v144, v144
	s_cmp_eq_u64 vcc, exec
	s_cselect_b64 s[0:1], -1, 0
	s_waitcnt vmcnt(4)
	v_cndmask_b32_e64 v144, v144, 1.0, s[0:1]
	v_cmp_gt_f32_e32 vcc, 1.0, v144
	ds_write_b128 v171, v[136:139] offset:49152
	ds_write_b128 v172, v[140:143] offset:49152
	s_cbranch_vccz .LBB0_717
	s_and_saveexec_b64 s[22:23], s[6:7]
	ds_write_b32 v166, v144 offset:128
	s_or_b64 exec, exec, s[22:23]
	s_waitcnt lgkmcnt(0)
	v_add_u32_e32 v140, v161, v178
	ds_read_b128 v[128:131], v140 offset:224
	ds_read_b128 v[132:135], v140 offset:192
	ds_read_b128 v[136:139], v140 offset:160
	ds_read_b128 v[140:143], v140 offset:128
	s_waitcnt lgkmcnt(3)
	v_pk_mul_f32 v[44:45], v[44:45], v[128:129]
	s_waitcnt lgkmcnt(2)
	v_pk_mul_f32 v[40:41], v[40:41], v[132:133]
	s_waitcnt lgkmcnt(1)
	v_pk_mul_f32 v[36:37], v[36:37], v[136:137]
	v_pk_mul_f32 v[46:47], v[46:47], v[130:131]
	v_pk_mul_f32 v[42:43], v[42:43], v[134:135]
	v_pk_mul_f32 v[38:39], v[38:39], v[138:139]
	s_waitcnt lgkmcnt(0)
	v_pk_mul_f32 v[34:35], v[34:35], v[142:143]
	v_pk_mul_f32 v[32:33], v[32:33], v[140:141]
	v_pk_mul_f32 v[60:61], v[60:61], v[128:129]
	v_pk_mul_f32 v[56:57], v[56:57], v[132:133]
	v_pk_mul_f32 v[52:53], v[52:53], v[136:137]
	v_pk_mul_f32 v[62:63], v[62:63], v[130:131]
	v_pk_mul_f32 v[58:59], v[58:59], v[134:135]
	v_pk_mul_f32 v[54:55], v[54:55], v[138:139]
	v_pk_mul_f32 v[50:51], v[50:51], v[142:143]
	v_pk_mul_f32 v[48:49], v[48:49], v[140:141]
	v_pk_mul_f32 v[28:29], v[28:29], v[128:129]
	v_pk_mul_f32 v[24:25], v[24:25], v[132:133]
	v_pk_mul_f32 v[20:21], v[20:21], v[136:137]
	v_pk_mul_f32 v[30:31], v[30:31], v[130:131]
	v_pk_mul_f32 v[26:27], v[26:27], v[134:135]
	v_pk_mul_f32 v[22:23], v[22:23], v[138:139]
	v_pk_mul_f32 v[18:19], v[18:19], v[142:143]
	v_pk_mul_f32 v[16:17], v[16:17], v[140:141]
	v_pk_mul_f32 v[12:13], v[12:13], v[128:129]
	v_pk_mul_f32 v[8:9], v[8:9], v[132:133]
	v_pk_mul_f32 v[4:5], v[4:5], v[136:137]
	v_pk_mul_f32 v[14:15], v[14:15], v[130:131]
	v_pk_mul_f32 v[10:11], v[10:11], v[134:135]
	v_pk_mul_f32 v[6:7], v[6:7], v[138:139]
	v_pk_mul_f32 v[2:3], v[2:3], v[142:143]
	v_pk_mul_f32 v[0:1], v[0:1], v[140:141]
.LBB0_717:
	v_cndmask_b32_e64 v148, v145, v200, s[0:1]
	v_mul_f32_e32 v128, 0xbe38aa3b, v148
	v_mov_b32_e32 v129, v128
	v_fmamk_f32 v80, v80, 0x3e38aa3b, v128
	v_fmamk_f32 v81, v81, 0x3e38aa3b, v128
	v_fmamk_f32 v82, v82, 0x3e38aa3b, v128
	v_fmamk_f32 v83, v83, 0x3e38aa3b, v128
	v_fmamk_f32 v84, v84, 0x3e38aa3b, v128
	v_fmamk_f32 v85, v85, 0x3e38aa3b, v128
	v_fmamk_f32 v86, v86, 0x3e38aa3b, v128
	v_fmamk_f32 v87, v87, 0x3e38aa3b, v128
	v_fmamk_f32 v88, v88, 0x3e38aa3b, v128
	v_fmamk_f32 v89, v89, 0x3e38aa3b, v128
	v_fmamk_f32 v90, v90, 0x3e38aa3b, v128
	v_fmamk_f32 v91, v91, 0x3e38aa3b, v128
	v_fmamk_f32 v92, v92, 0x3e38aa3b, v128
	v_fmamk_f32 v93, v93, 0x3e38aa3b, v128
	v_fmamk_f32 v94, v94, 0x3e38aa3b, v128
	v_fmac_f32_e32 v129, 0x3e38aa3b, v95
	v_exp_f32_e32 v145, v80
	v_exp_f32_e32 v158, v81
	v_exp_f32_e32 v146, v82
	v_exp_f32_e32 v159, v83
	v_exp_f32_e32 v147, v84
	v_exp_f32_e32 v200, v85
	v_exp_f32_e32 v157, v86
	v_exp_f32_e32 v203, v87
	v_exp_f32_e32 v149, v88
	v_exp_f32_e32 v153, v89
	v_exp_f32_e32 v150, v90
	v_exp_f32_e32 v154, v91
	v_exp_f32_e32 v151, v92
	v_exp_f32_e32 v155, v93
	v_exp_f32_e32 v152, v94
	v_exp_f32_e32 v156, v129
	v_pk_fma_f32 v[142:143], v[64:65], s[68:69], v[128:129] op_sel_hi:[1,0,0]
	v_add_f32_e32 v64, v189, v198
	v_fmac_f32_e32 v64, v188, v167
	v_add_f32_e32 v167, v201, v202
	v_pk_fma_f32 v[140:141], v[66:67], s[68:69], v[128:129] op_sel_hi:[1,0,0]
	v_pk_fma_f32 v[136:137], v[68:69], s[68:69], v[128:129] op_sel_hi:[1,0,0]
	v_pk_fma_f32 v[132:133], v[70:71], s[68:69], v[128:129] op_sel_hi:[1,0,0]
	v_pk_fma_f32 v[130:131], v[72:73], s[68:69], v[128:129] op_sel_hi:[1,0,0]
	v_pk_fma_f32 v[138:139], v[74:75], s[68:69], v[128:129] op_sel_hi:[1,0,0]
	v_pk_fma_f32 v[134:135], v[76:77], s[68:69], v[128:129] op_sel_hi:[1,0,0]
	v_pk_fma_f32 v[128:129], v[78:79], s[68:69], v[128:129] op_sel_hi:[1,0,0]
	v_fmac_f32_e32 v167, v64, v199
	s_add_i32 s30, s30, 2
	v_lshl_add_u64 v[162:163], v[162:163], 0, s[66:67]
	s_and_b64 vcc, exec, s[20:21]
	s_waitcnt lgkmcnt(0)
	s_barrier
	s_cbranch_vccnz .LBB0_719
	v_mov_b32_e32 v188, v144
	ds_write_b128 v173, v[240:243] offset:16384
	ds_write_b128 v174, v[244:247] offset:16384
	s_branch .LBB0_707

.LBB0_719:
	ds_write_b128 v173, v[240:243] offset:16384
	ds_write_b128 v174, v[244:247] offset:16384
	ds_read_b128 v[64:67], v170 offset:49152
	ds_read_b128 v[68:71], v170 offset:57344
	v_exp_f32_e32 v116, v138
	v_exp_f32_e32 v117, v139
	v_exp_f32_e32 v118, v134
	s_waitcnt lgkmcnt(1)
	v_mfma_f32_32x32x16_bf16 v[80:95], v[64:67], v[100:103], 0
	v_exp_f32_e32 v119, v135
	v_exp_f32_e32 v120, v128
	v_exp_f32_e32 v121, v129
	s_waitcnt lgkmcnt(0)
	v_mfma_f32_32x32x16_bf16 v[64:79], v[68:71], v[100:103], 0
	ds_read_b128 v[100:103], v186 offset:49152
	ds_read_b128 v[112:115], v186 offset:57344
	s_waitcnt lgkmcnt(1)
	v_mfma_f32_32x32x16_bf16 v[80:95], v[100:103], v[108:111], v[80:95]
	s_waitcnt lgkmcnt(0)
	v_mfma_f32_32x32x16_bf16 v[64:79], v[112:115], v[108:111], v[64:79]
	ds_read_b128 v[100:103], v175 offset:49152
	ds_read_b128 v[108:111], v175 offset:57344
	v_exp_f32_e32 v112, v132
	v_exp_f32_e32 v113, v133
	v_exp_f32_e32 v114, v130
	v_exp_f32_e32 v115, v131
	s_waitcnt lgkmcnt(1)
	v_mfma_f32_32x32x16_bf16 v[80:95], v[100:103], v[96:99], v[80:95]
	s_waitcnt lgkmcnt(0)
	v_mfma_f32_32x32x16_bf16 v[64:79], v[108:111], v[96:99], v[64:79]
	ds_read_b128 v[96:99], v187 offset:49152
	ds_read_b128 v[100:103], v187 offset:57344
	v_exp_f32_e32 v108, v140
	v_exp_f32_e32 v109, v141
	v_exp_f32_e32 v110, v136
	v_exp_f32_e32 v111, v137
	s_waitcnt lgkmcnt(1)
	v_mfma_f32_32x32x16_bf16 v[80:95], v[96:99], v[104:107], v[80:95]
	v_add_f32_e32 v96, 0, v145
	v_add_f32_e32 v96, v158, v96
	v_add_f32_e32 v96, v146, v96
	v_add_f32_e32 v96, v159, v96
	v_add_f32_e32 v96, v147, v96
	v_add_f32_e32 v96, v200, v96
	v_add_f32_e32 v96, v157, v96
	v_add_f32_e32 v96, v203, v96
	v_add_f32_e32 v96, v149, v96
	v_add_f32_e32 v96, v153, v96
	v_add_f32_e32 v96, v150, v96
	v_add_f32_e32 v96, v154, v96
	s_waitcnt lgkmcnt(0)
	v_mfma_f32_32x32x16_bf16 v[64:79], v[100:103], v[104:107], v[64:79]
	v_exp_f32_e32 v106, v142
	v_add_f32_e32 v96, v151, v96
	v_exp_f32_e32 v107, v143
	v_add_f32_e32 v96, v155, v96
	v_add_f32_e32 v96, v152, v96
	v_add_f32_e32 v96, v156, v96
	v_add_f32_e32 v96, v106, v96
	v_add_f32_e32 v96, v107, v96
	v_add_f32_e32 v96, v108, v96
	v_add_f32_e32 v96, v109, v96
	v_add_f32_e32 v96, v110, v96
	v_add_f32_e32 v96, v111, v96
	v_add_f32_e32 v96, v112, v96
	v_add_f32_e32 v96, v113, v96
	v_add_f32_e32 v96, v114, v96
	v_add_f32_e32 v96, v115, v96
	v_add_f32_e32 v96, v116, v96
	v_add_f32_e32 v96, v117, v96
	v_add_f32_e32 v96, v118, v96
	v_add_f32_e32 v96, v119, v96
	v_add_f32_e32 v96, v120, v96
	v_add_f32_e32 v96, v121, v96
	v_mov_b32_e32 v97, v96
	v_cvt_pk_bf16_f32 v98, v145, v158
	v_cvt_pk_bf16_f32 v99, v146, v159
	v_cvt_pk_bf16_f32 v100, v147, v200
	v_cvt_pk_bf16_f32 v101, v157, v203
	s_nop 1
	v_permlane32_swap_b32_e32 v96, v97
	v_permlane32_swap_b32_e32 v98, v100
	v_permlane32_swap_b32_e32 v99, v101
	v_cvt_pk_bf16_f32 v102, v149, v153
	v_cvt_pk_bf16_f32 v103, v150, v154
	v_cvt_pk_bf16_f32 v104, v151, v155
	v_cvt_pk_bf16_f32 v105, v152, v156
	v_cvt_pk_bf16_f32 v106, v106, v107
	v_cvt_pk_bf16_f32 v107, v108, v109
	v_cvt_pk_bf16_f32 v108, v110, v111
	v_cvt_pk_bf16_f32 v109, v112, v113
	v_cvt_pk_bf16_f32 v110, v114, v115
	v_cvt_pk_bf16_f32 v111, v116, v117
	v_cvt_pk_bf16_f32 v112, v118, v119
	v_cvt_pk_bf16_f32 v113, v120, v121
	s_nop 0
	v_permlane32_swap_b32_e32 v102, v104
	v_permlane32_swap_b32_e32 v103, v105
	v_permlane32_swap_b32_e32 v106, v108
	v_permlane32_swap_b32_e32 v107, v109
	v_permlane32_swap_b32_e32 v110, v112
	v_permlane32_swap_b32_e32 v111, v113
	ds_read_b64_tr_b16 v[114:115], v169 offset:0
	ds_read_b64_tr_b16 v[116:117], v169 offset:0x800
	ds_read_b64_tr_b16 v[118:119], v169 offset:0x1000
	ds_read_b64_tr_b16 v[120:121], v169 offset:0x1800
	ds_read_b64_tr_b16 v[122:123], v169 offset:0x2000
	ds_read_b64_tr_b16 v[124:125], v169 offset:0x2800
	ds_read_b64_tr_b16 v[126:127], v169 offset:0x3000
	ds_read_b64_tr_b16 v[128:129], v169 offset:0x3800
	s_nop 0
	s_waitcnt lgkmcnt(6)
	v_mfma_f32_32x32x16_bf16 v[32:47], v[98:101], v[114:117], v[32:47]
	ds_read_b64_tr_b16 v[114:115], v169 offset:0x200
	ds_read_b64_tr_b16 v[116:117], v169 offset:0xa00
	s_waitcnt lgkmcnt(6)
	v_mfma_f32_32x32x16_bf16 v[32:47], v[102:105], v[118:121], v[32:47]
	ds_read_b64_tr_b16 v[118:119], v169 offset:0x1200
	ds_read_b64_tr_b16 v[120:121], v169 offset:0x1a00
	s_waitcnt lgkmcnt(6)
	v_mfma_f32_32x32x16_bf16 v[32:47], v[106:109], v[122:125], v[32:47]
	ds_read_b64_tr_b16 v[122:123], v169 offset:0x2200
	ds_read_b64_tr_b16 v[124:125], v169 offset:0x2a00
	s_waitcnt lgkmcnt(6)
	v_mfma_f32_32x32x16_bf16 v[32:47], v[110:113], v[126:129], v[32:47]
	ds_read_b64_tr_b16 v[126:127], v169 offset:0x3200
	ds_read_b64_tr_b16 v[128:129], v169 offset:0x3a00
	s_waitcnt lgkmcnt(6)
	v_mfma_f32_32x32x16_bf16 v[48:63], v[98:101], v[114:117], v[48:63]
	ds_read_b64_tr_b16 v[114:115], v169 offset:0x400
	ds_read_b64_tr_b16 v[116:117], v169 offset:0xc00
	s_waitcnt lgkmcnt(6)
	v_mfma_f32_32x32x16_bf16 v[48:63], v[102:105], v[118:121], v[48:63]
	ds_read_b64_tr_b16 v[118:119], v169 offset:0x1400
	ds_read_b64_tr_b16 v[120:121], v169 offset:0x1c00
	s_waitcnt lgkmcnt(6)
	v_mfma_f32_32x32x16_bf16 v[48:63], v[106:109], v[122:125], v[48:63]
	ds_read_b64_tr_b16 v[122:123], v169 offset:0x2400
	ds_read_b64_tr_b16 v[124:125], v169 offset:0x2c00
	s_waitcnt lgkmcnt(6)
	v_mfma_f32_32x32x16_bf16 v[48:63], v[110:113], v[126:129], v[48:63]
	ds_read_b64_tr_b16 v[126:127], v169 offset:0x3400
	ds_read_b64_tr_b16 v[128:129], v169 offset:0x3c00
	s_waitcnt lgkmcnt(6)
	v_mfma_f32_32x32x16_bf16 v[16:31], v[98:101], v[114:117], v[16:31]
	ds_read_b64_tr_b16 v[114:115], v169 offset:0x600
	ds_read_b64_tr_b16 v[116:117], v169 offset:0xe00
	s_waitcnt lgkmcnt(6)
	v_mfma_f32_32x32x16_bf16 v[16:31], v[102:105], v[118:121], v[16:31]
	ds_read_b64_tr_b16 v[118:119], v169 offset:0x1600
	ds_read_b64_tr_b16 v[120:121], v169 offset:0x1e00
	s_waitcnt lgkmcnt(6)
	v_mfma_f32_32x32x16_bf16 v[16:31], v[106:109], v[122:125], v[16:31]
	ds_read_b64_tr_b16 v[122:123], v169 offset:0x2600
	ds_read_b64_tr_b16 v[124:125], v169 offset:0x2e00
	s_waitcnt lgkmcnt(6)
	v_mfma_f32_32x32x16_bf16 v[16:31], v[110:113], v[126:129], v[16:31]
	ds_read_b64_tr_b16 v[126:127], v169 offset:0x3600
	ds_read_b64_tr_b16 v[128:129], v169 offset:0x3e00
	s_waitcnt lgkmcnt(6)
	v_mfma_f32_32x32x16_bf16 v[0:15], v[98:101], v[114:117], v[0:15]
	v_max_f32_e32 v98, v81, v81
	v_max_f32_e32 v99, v80, v80
	v_max_f32_e32 v98, v99, v98
	v_max3_f32 v98, v98, v82, v83
	v_max3_f32 v98, v98, v84, v85
	v_max3_f32 v98, v98, v86, v87
	v_max3_f32 v98, v98, v88, v89
	v_max3_f32 v98, v98, v90, v91
	v_max3_f32 v98, v98, v92, v93
	s_waitcnt lgkmcnt(4)
	v_mfma_f32_32x32x16_bf16 v[0:15], v[102:105], v[118:121], v[0:15]
	v_max3_f32 v98, v98, v94, v95
	v_max3_f32 v98, v98, v64, v65
	v_max3_f32 v98, v98, v66, v67
	v_max3_f32 v98, v98, v68, v69
	v_max3_f32 v98, v98, v70, v71
	v_max3_f32 v98, v98, v72, v73
	v_max3_f32 v98, v98, v74, v75
	v_max3_f32 v98, v98, v76, v77
	s_waitcnt lgkmcnt(2)
	v_mfma_f32_32x32x16_bf16 v[0:15], v[106:109], v[122:125], v[0:15]
	v_max3_f32 v98, v98, v78, v79
	v_mov_b32_e32 v99, v98
	s_nop 1
	v_permlane32_swap_b32_e32 v98, v99
	v_max_f32_e32 v99, v99, v99
	v_max_f32_e32 v98, v98, v98
	v_max_f32_e32 v98, v98, v99
	v_sub_f32_e32 v99, v98, v148
	v_cmp_ge_f32_e32 vcc, s26, v99
	v_max_f32_e32 v99, v148, v148
	v_max_f32_e32 v99, v99, v98
	s_waitcnt lgkmcnt(0)
	v_mfma_f32_32x32x16_bf16 v[0:15], v[110:113], v[126:129], v[0:15]
	v_sub_f32_e32 v98, v148, v99
	v_mul_f32_e32 v98, 0x3e38aa3b, v98
	v_exp_f32_e32 v98, v98
	s_cmp_eq_u64 vcc, exec
	s_cselect_b64 s[0:1], -1, 0
	v_cndmask_b32_e64 v98, v98, 1.0, s[0:1]
	v_cmp_gt_f32_e32 vcc, 1.0, v98
	s_barrier
	s_cbranch_vccz .LBB0_723
	s_and_saveexec_b64 s[20:21], s[6:7]
	s_movk_i32 s89, 0x2000
	ds_write_b32 v166, v98 offset:128
	s_or_b64 exec, exec, s[20:21]
	s_waitcnt lgkmcnt(0)
	v_add_u32_e32 v112, v161, v178
	ds_read_b128 v[100:103], v112 offset:224
	ds_read_b128 v[104:107], v112 offset:192
	ds_read_b128 v[108:111], v112 offset:160
	ds_read_b128 v[112:115], v112 offset:128
	s_waitcnt lgkmcnt(3)
	v_pk_mul_f32 v[44:45], v[44:45], v[100:101]
	s_waitcnt lgkmcnt(2)
	v_pk_mul_f32 v[40:41], v[40:41], v[104:105]
	s_waitcnt lgkmcnt(1)
	v_pk_mul_f32 v[36:37], v[36:37], v[108:109]
	v_pk_mul_f32 v[46:47], v[46:47], v[102:103]
	v_pk_mul_f32 v[42:43], v[42:43], v[106:107]
	v_pk_mul_f32 v[38:39], v[38:39], v[110:111]
	s_waitcnt lgkmcnt(0)
	v_pk_mul_f32 v[34:35], v[34:35], v[114:115]
	v_pk_mul_f32 v[32:33], v[32:33], v[112:113]
	v_pk_mul_f32 v[60:61], v[60:61], v[100:101]
	v_pk_mul_f32 v[56:57], v[56:57], v[104:105]
	v_pk_mul_f32 v[52:53], v[52:53], v[108:109]
	v_pk_mul_f32 v[62:63], v[62:63], v[102:103]
	v_pk_mul_f32 v[58:59], v[58:59], v[106:107]
	v_pk_mul_f32 v[54:55], v[54:55], v[110:111]
	v_pk_mul_f32 v[50:51], v[50:51], v[114:115]
	v_pk_mul_f32 v[48:49], v[48:49], v[112:113]
	v_pk_mul_f32 v[28:29], v[28:29], v[100:101]
	v_pk_mul_f32 v[24:25], v[24:25], v[104:105]
	v_pk_mul_f32 v[20:21], v[20:21], v[108:109]
	v_pk_mul_f32 v[30:31], v[30:31], v[102:103]
	v_pk_mul_f32 v[26:27], v[26:27], v[106:107]
	v_pk_mul_f32 v[22:23], v[22:23], v[110:111]
	v_pk_mul_f32 v[18:19], v[18:19], v[114:115]
	v_pk_mul_f32 v[16:17], v[16:17], v[112:113]
	v_pk_mul_f32 v[12:13], v[12:13], v[100:101]
	v_pk_mul_f32 v[8:9], v[8:9], v[104:105]
	v_pk_mul_f32 v[4:5], v[4:5], v[108:109]
	v_pk_mul_f32 v[14:15], v[14:15], v[102:103]
	v_pk_mul_f32 v[10:11], v[10:11], v[106:107]
	v_pk_mul_f32 v[6:7], v[6:7], v[110:111]
	v_pk_mul_f32 v[2:3], v[2:3], v[114:115]
	v_pk_mul_f32 v[0:1], v[0:1], v[112:113]
	s_branch .LBB0_724
